# mLSTM step: q.n and state-update LDS fragment reads issued ahead of their consumers with counted lgkmcnt
# baseline (speedup 1.0000x reference)
.LBB0_1693:
	v_ashrrev_i32_e32 v99, 3, v80
	v_lshlrev_b32_e32 v0, 4, v8
	v_and_b32_e32 v84, 0x70, v0
	v_mul_lo_u32 v0, v99, s69
	s_waitcnt lgkmcnt(0)
	s_barrier
	v_lshl_add_u32 v0, v84, 1, v0
	ds_read_b128 v[10:13], v0 offset:54272
	ds_read_b128 v[32:35], v0 offset:54288
	v_lshlrev_b32_e32 v5, 2, v84
	v_or_b32_e32 v6, 0x21400, v5
	ds_read_b128 v[118:121], v6
	ds_read_b128 v[122:125], v6 offset:16
	ds_read_b128 v[200:203], v6 offset:32
	ds_read_b128 v[204:207], v6 offset:48
	v_add_u32_e32 v7, 0x11800, v0
	s_waitcnt lgkmcnt(5)
	v_lshlrev_b32_e32 v0, 16, v10
	v_and_b32_e32 v9, 0xffff0000, v10
	v_or_b32_e32 v10, 0x21410, v5
	v_lshlrev_b32_e32 v14, 16, v11
	v_and_b32_e32 v15, 0xffff0000, v11
	v_lshlrev_b32_e32 v40, 16, v12
	v_and_b32_e32 v41, 0xffff0000, v12
	ds_read_b64 v[82:83], v90
	v_lshlrev_b32_e32 v6, 16, v13
	v_and_b32_e32 v42, 0xffff0000, v13
	s_cmp_gt_u32 s77, 1
	s_waitcnt lgkmcnt(4)
	v_mul_f32_e32 v0, v118, v0
	v_mul_f32_e32 v9, v119, v9
	v_mul_f32_e32 v14, v120, v14
	s_waitcnt lgkmcnt(3)
	v_mul_f32_e32 v36, v122, v40
	v_mul_f32_e32 v13, v125, v42
	v_cvt_pk_bf16_f32 v10, v0, v9
	v_mul_f32_e32 v15, v121, v15
	v_mul_f32_e32 v37, v123, v41
	v_mul_f32_e32 v6, v124, v6
	v_cvt_pk_bf16_f32 v11, v14, v15
	v_cvt_pk_bf16_f32 v12, v36, v37
	v_cvt_pk_bf16_f32 v13, v6, v13
	ds_write_b128 v7, v[10:13]
	v_or_b32_e32 v10, 0x21420, v5
	v_or_b32_e32 v5, 0x21430, v5
	v_lshlrev_b32_e32 v0, 16, v32
	v_and_b32_e32 v6, 0xffff0000, v32
	v_lshlrev_b32_e32 v9, 16, v33
	v_and_b32_e32 v14, 0xffff0000, v33
	v_lshlrev_b32_e32 v15, 16, v34
	v_and_b32_e32 v36, 0xffff0000, v34
	v_lshlrev_b32_e32 v37, 16, v35
	v_and_b32_e32 v38, 0xffff0000, v35
	s_cselect_b64 s[54:55], -1, 0
	s_cmp_lt_u32 s77, 2
	v_ashrrev_i32_e32 v100, 5, v8
	v_and_b32_e32 v101, 31, v8
	s_waitcnt lgkmcnt(3)
	v_mul_f32_e32 v5, v201, v6
	v_mul_f32_e32 v6, v202, v9
	v_mul_f32_e32 v9, v203, v14
	s_waitcnt lgkmcnt(2)
	v_mul_f32_e32 v12, v204, v15
	v_mul_f32_e32 v13, v205, v36
	v_mul_f32_e32 v0, v200, v0
	v_mul_f32_e32 v14, v206, v37
	v_mul_f32_e32 v15, v207, v38
	v_cvt_pk_bf16_f32 v10, v0, v5
	v_cvt_pk_bf16_f32 v11, v6, v9
	v_cvt_pk_bf16_f32 v12, v12, v13
	v_cvt_pk_bf16_f32 v13, v14, v15
	ds_write_b128 v7, v[10:13] offset:16
	s_cbranch_scc1 .LBB0_1723
	v_lshlrev_b32_e32 v178, 2, v3
	v_or_b32_e32 v177, 0x21600, v178
	ds_read_b128 v[208:211], v4
	ds_read_b128 v[212:215], v177
	ds_read_b128 v[216:219], v4 offset:16
	ds_read_b128 v[220:223], v177 offset:16
	ds_read_b128 v[224:227], v177 offset:32
	ds_read_b128 v[228:231], v177 offset:48
	v_lshlrev_b32_e32 v0, 2, v3
	v_or_b32_e32 v3, 0x21600, v0
	s_nop 0
	s_waitcnt lgkmcnt(5)
	v_lshlrev_b32_e32 v9, 16, v208
	v_and_b32_e32 v14, 0xffff0000, v208
	v_add_u32_e32 v10, 0x21610, v0
	v_lshlrev_b32_e32 v15, 16, v209
	v_and_b32_e32 v36, 0xffff0000, v209
	v_lshlrev_b32_e32 v37, 16, v210
	v_and_b32_e32 v38, 0xffff0000, v210
	v_lshlrev_b32_e32 v3, 16, v211
	v_and_b32_e32 v39, 0xffff0000, v211
	s_nop 0
	s_waitcnt lgkmcnt(4)
	v_mul_f32_e32 v14, v213, v14
	v_fmac_f32_e32 v14, v212, v9
	v_fmac_f32_e32 v14, v214, v15
	v_fmac_f32_e32 v14, v215, v36
	s_nop 0
	s_waitcnt lgkmcnt(2)
	v_fmac_f32_e32 v14, v220, v37
	v_fmac_f32_e32 v14, v221, v38
	v_fmac_f32_e32 v14, v222, v3
	v_fmac_f32_e32 v14, v223, v39
	v_add_f32_e32 v3, 0, v14
	v_lshlrev_b32_e32 v9, 16, v216
	v_and_b32_e32 v14, 0xffff0000, v216
	v_add_u32_e32 v4, 0x21620, v0
	v_add_u32_e32 v0, 0x21630, v0
	v_lshlrev_b32_e32 v15, 16, v217
	v_and_b32_e32 v32, 0xffff0000, v217
	v_lshlrev_b32_e32 v33, 16, v218
	v_and_b32_e32 v34, 0xffff0000, v218
	v_lshlrev_b32_e32 v35, 16, v219
	v_and_b32_e32 v36, 0xffff0000, v219
	s_nop 0
	s_waitcnt lgkmcnt(1)
	v_mul_f32_e32 v0, v225, v14
	v_fmac_f32_e32 v0, v224, v9
	v_fmac_f32_e32 v0, v226, v15
	v_fmac_f32_e32 v0, v227, v32
	s_nop 0
	s_waitcnt lgkmcnt(0)
	v_fmac_f32_e32 v0, v228, v33
	v_fmac_f32_e32 v0, v229, v34
	v_fmac_f32_e32 v0, v230, v35
	v_fmac_f32_e32 v0, v231, v36
	v_and_b32_e32 v4, 64, v91
	v_add_f32_e32 v0, v3, v0
	v_xor_b32_e32 v3, 1, v91
	v_add_u32_e32 v9, 64, v4
	v_cmp_lt_i32_e32 vcc, v3, v9
	s_nop 1
	v_cndmask_b32_e32 v3, v91, v3, vcc
	v_lshlrev_b32_e32 v3, 2, v3
	ds_bpermute_b32 v3, v3, v0
	s_waitcnt lgkmcnt(0)
	v_add_f32_e32 v0, v0, v3
	v_xor_b32_e32 v3, 2, v91
	v_cmp_lt_i32_e32 vcc, v3, v9
	s_nop 1
	v_cndmask_b32_e32 v3, v91, v3, vcc
	v_lshlrev_b32_e32 v3, 2, v3
	ds_bpermute_b32 v3, v3, v0
	v_cmp_eq_u32_e32 vcc, 0, v85
	s_and_saveexec_b64 s[10:11], vcc
	s_cbranch_execz .LBB0_1696
	s_waitcnt lgkmcnt(0)
	v_add_f32_e32 v0, v0, v3
	v_lshl_add_u32 v2, v2, 2, v92
	ds_write_b32 v2, v0

.LBB0_1740:
	v_or_b32_e32 v2, s35, v101
	v_mul_lo_u32 v2, v2, s69
	v_lshlrev_b32_e32 v6, 4, v100
	v_add3_u32 v14, v2, v6, s72
	s_waitcnt lgkmcnt(0)
	v_or_b32_e32 v178, s39, v101
	v_mad_u32_u24 v177, v178, s69, v6
	ds_read_b128 v[200:203], v14
	ds_read_b128 v[204:207], v177 offset:36864
	ds_read_b128 v[208:211], v14 offset:32
	ds_read_b128 v[212:215], v177 offset:36896
	ds_read_b128 v[216:219], v14 offset:64
	ds_read_b128 v[220:223], v177 offset:36928
	ds_read_b128 v[224:227], v177 offset:36960
	ds_read_b128 v[228:231], v14 offset:96
	ds_read_b128 v[232:235], v14 offset:128
	ds_read_b128 v[236:239], v177 offset:36992
	ds_read_b128 v[240:243], v177 offset:37024
	ds_read_b128 v[244:247], v14 offset:160
	ds_read_b128 v[118:121], v14 offset:192
	ds_read_b128 v[122:125], v177 offset:37056
	ds_read_b128 v[160:163], v177 offset:37088
	ds_read_b128 v[164:167], v14 offset:224
	v_or_b32_e32 v7, s39, v101
	v_mad_u32_u24 v15, v7, s69, v6
	v_mov_b32_e32 v0, v83
	v_pk_mul_f32 v[30:31], v[30:31], v[0:1] op_sel_hi:[1, 0]
	v_pk_mul_f32 v[28:29], v[28:29], v[0:1] op_sel_hi:[1, 0]
	v_pk_mul_f32 v[26:27], v[26:27], v[0:1] op_sel_hi:[1, 0]
	v_pk_mul_f32 v[24:25], v[24:25], v[0:1] op_sel_hi:[1, 0]
	v_pk_mul_f32 v[22:23], v[22:23], v[0:1] op_sel_hi:[1, 0]
	v_pk_mul_f32 v[20:21], v[20:21], v[0:1] op_sel_hi:[1, 0]
	v_pk_mul_f32 v[18:19], v[18:19], v[0:1] op_sel_hi:[1, 0]
	v_pk_mul_f32 v[16:17], v[16:17], v[0:1] op_sel_hi:[1, 0]
	s_nop 0
	s_waitcnt lgkmcnt(14)
	v_mfma_f32_32x32x16_bf16 v[16:31], v[200:203], v[204:207], v[16:31]
	v_lshl_add_u32 v0, v100, 2, s35
	v_mul_lo_u32 v0, v0, s68
	s_nop 0
	s_waitcnt lgkmcnt(12)
	v_mfma_f32_32x32x16_bf16 v[16:31], v[208:211], v[212:215], v[16:31]
	s_nop 0
	s_waitcnt lgkmcnt(10)
	v_mfma_f32_32x32x16_bf16 v[16:31], v[216:219], v[220:223], v[16:31]
	s_nop 0
	s_waitcnt lgkmcnt(8)
	v_mfma_f32_32x32x16_bf16 v[16:31], v[228:231], v[224:227], v[16:31]
	s_nop 0
	s_waitcnt lgkmcnt(6)
	v_mfma_f32_32x32x16_bf16 v[16:31], v[232:235], v[236:239], v[16:31]
	s_nop 0
	s_waitcnt lgkmcnt(4)
	v_mfma_f32_32x32x16_bf16 v[16:31], v[244:247], v[240:243], v[16:31]
	s_nop 0
	s_waitcnt lgkmcnt(2)
	v_mfma_f32_32x32x16_bf16 v[16:31], v[118:121], v[122:125], v[16:31]
	v_lshlrev_b32_e32 v2, 1, v101
	v_add3_u32 v0, s57, v2, v0
	s_nop 0
	s_waitcnt lgkmcnt(0)
	v_mfma_f32_32x32x16_bf16 v[16:31], v[164:167], v[160:163], v[16:31]
	s_nop 11
	v_bfe_u32 v2, v16, 16, 1
	v_bfe_u32 v3, v17, 16, 1
	v_bfe_u32 v4, v18, 16, 1
	v_bfe_u32 v5, v19, 16, 1
	v_bfe_u32 v6, v20, 16, 1
	v_bfe_u32 v7, v21, 16, 1
	v_bfe_u32 v8, v22, 16, 1
	v_bfe_u32 v9, v23, 16, 1
	v_bfe_u32 v10, v24, 16, 1
	v_bfe_u32 v11, v25, 16, 1
	v_bfe_u32 v12, v26, 16, 1
	v_bfe_u32 v13, v27, 16, 1
	v_add3_u32 v2, v16, v2, s73
	v_add3_u32 v3, v17, v3, s73
	v_add3_u32 v4, v18, v4, s73
	v_add3_u32 v5, v19, v5, s73
	v_add3_u32 v6, v20, v6, s73
	v_add3_u32 v7, v21, v7, s73
	v_add3_u32 v8, v22, v8, s73
	v_add3_u32 v9, v23, v9, s73
	v_add3_u32 v10, v24, v10, s73
	v_add3_u32 v11, v25, v11, s73
	v_add3_u32 v12, v26, v12, s73
	v_add3_u32 v13, v27, v13, s73
	ds_write_b16_d16_hi v0, v2
	ds_write_b16_d16_hi v0, v3 offset:144
	ds_write_b16_d16_hi v0, v4 offset:288
	ds_write_b16_d16_hi v0, v5 offset:432
	ds_write_b16_d16_hi v0, v6 offset:1152
	ds_write_b16_d16_hi v0, v7 offset:1296
	ds_write_b16_d16_hi v0, v8 offset:1440
	ds_write_b16_d16_hi v0, v9 offset:1584
	ds_write_b16_d16_hi v0, v10 offset:2304
	ds_write_b16_d16_hi v0, v11 offset:2448
	ds_write_b16_d16_hi v0, v12 offset:2592
	ds_write_b16_d16_hi v0, v13 offset:2736
	v_bfe_u32 v2, v28, 16, 1
	v_add3_u32 v2, v28, v2, s73
	ds_write_b16_d16_hi v0, v2 offset:3456
	v_bfe_u32 v2, v29, 16, 1
	v_add3_u32 v2, v29, v2, s73
	ds_write_b16_d16_hi v0, v2 offset:3600
	v_bfe_u32 v2, v30, 16, 1
	v_add3_u32 v2, v30, v2, s73
	ds_write_b16_d16_hi v0, v2 offset:3744
	v_bfe_u32 v2, v31, 16, 1
	v_add3_u32 v2, v31, v2, s73
	ds_write_b16_d16_hi v0, v2 offset:3888
